# phase 6 (post-attention residual + FFN pre-norm rows): next row's loads issued one row ahead into spare registers so the two wave reductions overlap the memory latency
# speedup vs baseline: 1.0027x; 1.0020x over previous
; DI void phase6(const Params& p) {
;     const int lane = VTID & 63, w = VTID >> 6;
;     const float* x = p.in[0]; const float* gpost = p.in[15]; const float* gffn = p.in[16];
;     const bf16_t* MIX = (const bf16_t*)(p.ws + OFF_MIX);
;     bf16_t* H = (bf16_t*)(p.ws + OFF_H);
;     float* RSTD = (float*)(p.ws + OFF_GATES);
;     for (int row = VBLK * 4 + w; row < T; row += VGRID * 4) {
;         f32x4 mv[4], xv[4]; float ss = 0.f;
; #pragma unroll
;         for (int i = 0; i < 4; ++i) {
;             const u32x2 u = *(const u32x2*)(MIX + (size_t)row * 1024 + i * 256 + lane * 4);
.LBB0_702:
	s_cmp_gt_i32 s90, 6
	s_cselect_b64 s[0:1], -1, 0
	s_cmp_lt_i32 s91, 7
	s_cselect_b64 s[2:3], -1, 0
	s_or_b64 s[0:1], s[0:1], s[2:3]
	v_bfe_u32 v1, v0, 6, 4
	s_and_b64 vcc, exec, s[0:1]
	v_and_b32_e32 v150, 4, v1
	s_cbranch_vccnz .LBB0_758
	v_and_b32_e32 v56, 0x3ff, v0
	v_readlane_b32 s0, v238, 0
	v_bfe_u32 v1, v56, 6, 2
	s_lshl_b32 s0, s0, 3
	v_or3_b32 v18, v150, s0, v1
	s_mov_b32 s0, 0x8000
	v_cmp_gt_i32_e32 vcc, s0, v18
	s_and_saveexec_b64 s[2:3], vcc
	s_cbranch_execz .LBB0_708
	v_mbcnt_lo_u32_b32 v2, -1, 0
	v_mbcnt_hi_u32_b32 v2, -1, v2
	v_and_b32_e32 v4, 64, v2
	v_xor_b32_e32 v3, 32, v2
	v_add_u32_e32 v4, 64, v4
	v_cmp_lt_i32_e32 vcc, v3, v4
	v_readlane_b32 s4, v238, 31
	v_readlane_b32 s5, v238, 32
	v_cndmask_b32_e32 v3, v2, v3, vcc
	v_lshlrev_b32_e32 v57, 2, v3
	v_xor_b32_e32 v3, 16, v2
	v_cmp_lt_i32_e32 vcc, v3, v4
	v_readlane_b32 s6, v238, 33
	v_readlane_b32 s7, v238, 34
	v_cndmask_b32_e32 v3, v2, v3, vcc
	v_lshlrev_b32_e32 v58, 2, v3
	v_xor_b32_e32 v3, 8, v2
	v_cmp_lt_i32_e32 vcc, v3, v4
	v_readlane_b32 s8, v238, 35
	v_readlane_b32 s9, v238, 36
	v_cndmask_b32_e32 v3, v2, v3, vcc
	v_lshlrev_b32_e32 v59, 2, v3
	v_xor_b32_e32 v3, 4, v2
	v_cmp_lt_i32_e32 vcc, v3, v4
	v_readlane_b32 s10, v238, 37
	v_readlane_b32 s11, v238, 38
	v_cndmask_b32_e32 v3, v2, v3, vcc
	v_lshlrev_b32_e32 v60, 2, v3
	v_xor_b32_e32 v3, 2, v2
	v_cmp_lt_i32_e32 vcc, v3, v4
	v_and_b32_e32 v1, 63, v56
	v_readlane_b32 s4, v238, 1
	v_cndmask_b32_e32 v3, v2, v3, vcc
	v_lshlrev_b32_e32 v61, 2, v3
	v_xor_b32_e32 v3, 1, v2
	v_cmp_lt_i32_e32 vcc, v3, v4
	v_readlane_b32 s12, v238, 39
	v_readlane_b32 s13, v238, 40
	v_cndmask_b32_e32 v2, v2, v3, vcc
	v_lshlrev_b32_e32 v62, 2, v2
	v_lshlrev_b32_e32 v2, 4, v1
	v_mov_b32_e32 v3, 0
	v_readlane_b32 s14, v238, 41
	v_readlane_b32 s15, v238, 42
	v_readlane_b32 s16, v238, 43
	v_readlane_b32 s17, v238, 44
	v_readlane_b32 s18, v238, 45
	v_readlane_b32 s19, v238, 46
	v_readlane_b32 s5, v238, 2
	v_ashrrev_i32_e32 v19, 31, v18
	v_mov_b64_e32 v[4:5], 0x18ba5800
	v_lshl_add_u64 v[20:21], s[18:19], 0, v[2:3]
	v_readlane_b32 s6, v238, 3
	v_lshl_add_u64 v[22:23], s[4:5], 0, v[2:3]
	v_readlane_b32 s4, v238, 10
	v_lshl_add_u64 v[24:25], v[18:19], 2, v[4:5]
	v_lshlrev_b64 v[4:5], 12, v[18:19]
	v_readlane_b32 s12, v238, 15
	v_readlane_b32 s7, v238, 4
	v_readlane_b32 s5, v238, 11
	s_lshl_b32 s6, s4, 3
	v_or_b32_e32 v4, v4, v2
	v_readlane_b32 s13, v238, 16
	v_readlane_b32 s8, v238, 5
	v_readlane_b32 s9, v238, 6
	v_readlane_b32 s10, v238, 7
	v_readlane_b32 s11, v238, 8
	s_ashr_i32 s7, s6, 31
	v_lshlrev_b64 v[26:27], 11, v[18:19]
	v_readlane_b32 s14, v238, 17
	v_readlane_b32 s15, v238, 18
	v_readlane_b32 s16, v238, 19
	v_readlane_b32 s17, v238, 20
	v_lshl_add_u64 v[2:3], s[12:13], 0, v[4:5]
	s_mov_b64 s[4:5], 0xc00
	v_cmp_eq_u32_e64 s[0:1], 0, v1
	s_lshl_b64 s[8:9], s[6:7], 2
	v_lshl_or_b32 v26, v1, 3, v26
	s_lshl_b64 s[10:11], s[6:7], 11
	v_lshl_add_u64 v[28:29], v[2:3], 0, s[4:5]
	s_lshl_b64 s[12:13], s[6:7], 12
	s_mov_b64 s[14:15], 0
	v_mov_b32_e32 v63, 0x358637bd
	s_mov_b32 s7, 0x800000
	s_mov_b32 s16, 0x1ba5000
	s_movk_i32 s17, 0x7fff
	v_readlane_b32 s18, v238, 21
	v_readlane_b32 s19, v238, 22
	v_readlane_b32 s20, v238, 23
	v_readlane_b32 s21, v238, 24
	v_readlane_b32 s22, v238, 25
	v_readlane_b32 s23, v238, 26
	v_readlane_b32 s24, v238, 27
	v_readlane_b32 s25, v238, 28
	v_readlane_b32 s26, v238, 29
	v_readlane_b32 s27, v238, 30
	global_load_dwordx4 v[200:203], v[20:21], off
	global_load_dwordx4 v[204:207], v[20:21], off offset:1024
	global_load_dwordx4 v[208:211], v[20:21], off offset:2048
	global_load_dwordx4 v[212:215], v[20:21], off offset:3072
	global_load_dwordx4 v[216:219], v[22:23], off
	global_load_dwordx4 v[220:223], v[22:23], off offset:1024
	global_load_dwordx4 v[224:227], v[22:23], off offset:2048
	global_load_dwordx4 v[228:231], v[22:23], off offset:3072
	v_lshl_add_u64 v[96:97], s[88:89], 0, v[26:27]
	v_add_co_u32_e32 v96, vcc, 0x9ba5000, v96
	s_nop 1
	v_addc_co_u32_e32 v97, vcc, 0, v97, vcc
	v_mov_b32_e32 v98, v28
	v_mov_b32_e32 v99, v29
	global_load_dwordx2 v[70:71], v[96:97], off offset:2048
	global_load_dwordx2 v[72:73], v[96:97], off offset:2560
	global_load_dwordx2 v[74:75], v[96:97], off offset:3072
	global_load_dwordx2 v[76:77], v[96:97], off offset:3584
	global_load_dwordx4 v[80:83], v[98:99], off offset:-3072
	global_load_dwordx4 v[84:87], v[98:99], off offset:-2048
	global_load_dwordx4 v[88:91], v[98:99], off offset:-1024
	global_load_dwordx4 v[92:95], v[98:99], off
	s_waitcnt vmcnt(0)
	s_branch .Lp6_in
; DI unsigned pk_bf16(float a, float b) { f32x2 v = {a, b}; return __builtin_bit_cast(unsigned, __builtin_convertvector(v, bf16v2)); }
; DI void phase6(const Params& p) {
;     ...
;         float ss2 = 0.f;
; #pragma unroll
;         for (int i = 0; i < 4; ++i) {
;             const f32x4 gg = *(const f32x4*)(gpost + i * 256 + lane * 4);
; #pragma unroll
;             for (int e = 0; e < 4; ++e) { xv[i][e] += mv[i][e] * rstd * gg[e]; ss2 += xv[i][e] * xv[i][e]; }
;         }
;         ss2 = wave_sum(ss2);
;         const float rstd2 = rsqrtf(ss2 * (1.f / 1024.f) + NORM_EPS);
; #pragma unroll
;         for (int i = 0; i < 4; ++i) {
;             const f32x4 gg = *(const f32x4*)(gffn + i * 256 + lane * 4);
;             u32x2 o; o.x = pk_bf16(xv[i][0] * rstd2 * gg[0], xv[i][1] * rstd2 * gg[1]); o.y = pk_bf16(xv[i][2] * rstd2 * gg[2], xv[i][3] * rstd2 * gg[3]);
;             *(u32x2*)(H + (size_t)row * 1024 + i * 256 + lane * 4) = o;
;         }
.LBB0_705:
	s_or_b64 exec, exec, s[4:5]
	v_mov_b32_e32 v39, v51
	v_mov_b32_e32 v41, v45
	v_mov_b32_e32 v45, v53
	v_mov_b32_e32 v33, v1
	v_mov_b32_e32 v35, v19
	v_mov_b32_e32 v43, v47
	v_pk_mul_f32 v[32:33], v[48:49], v[32:33] op_sel_hi:[0,1]
	v_pk_mul_f32 v[34:35], v[48:49], v[34:35] op_sel_hi:[0,1]
	v_pk_mul_f32 v[42:43], v[48:49], v[42:43] op_sel_hi:[0,1]
	v_mov_b32_e32 v37, v49
	v_pk_mul_f32 v[40:41], v[48:49], v[40:41] op_sel_hi:[0,1]
	v_pk_mul_f32 v[36:37], v[48:49], v[36:37] op_sel_hi:[0,1]
	v_pk_mul_f32 v[38:39], v[48:49], v[38:39] op_sel_hi:[0,1]
	v_mov_b32_e32 v47, v55
	v_pk_mul_f32 v[44:45], v[48:49], v[44:45] op_sel_hi:[0,1]
	v_pk_mul_f32 v[46:47], v[48:49], v[46:47] op_sel_hi:[0,1]
	v_add_co_u32_e64 v30, s[4:5], s16, v30
	v_add_u32_e32 v18, s6, v18
	s_nop 0
	v_addc_co_u32_e64 v31, s[4:5], 0, v31, s[4:5]
	v_lshl_add_u64 v[24:25], v[24:25], 0, s[8:9]
	v_lshl_add_u64 v[26:27], v[26:27], 0, s[10:11]
	v_lshl_add_u64 v[28:29], v[28:29], 0, s[12:13]
	v_pk_fma_f32 v[14:15], v[32:33], v[200:201], v[14:15]
	v_pk_fma_f32 v[16:17], v[34:35], v[202:203], v[16:17]
	v_pk_fma_f32 v[32:33], v[42:43], v[210:211], v[4:5]
	v_pk_mul_f32 v[4:5], v[14:15], v[14:15]
	v_pk_fma_f32 v[34:35], v[40:41], v[208:209], v[2:3]
	v_pk_mul_f32 v[2:3], v[16:17], v[16:17]
	v_add_f32_e32 v1, v4, v5
	v_pk_fma_f32 v[10:11], v[36:37], v[204:205], v[10:11]
	v_add_f32_e32 v1, v2, v1
	v_pk_fma_f32 v[12:13], v[38:39], v[206:207], v[12:13]
	v_pk_mul_f32 v[38:39], v[10:11], v[10:11]
	v_add_f32_e32 v1, v3, v1
	v_add_f32_e32 v1, v38, v1
	v_pk_mul_f32 v[36:37], v[12:13], v[12:13]
	v_add_f32_e32 v1, v39, v1
	v_add_f32_e32 v1, v36, v1
	v_pk_mul_f32 v[42:43], v[34:35], v[34:35]
	v_add_f32_e32 v1, v37, v1
	v_add_f32_e32 v1, v42, v1
	v_pk_mul_f32 v[40:41], v[32:33], v[32:33]
	v_add_f32_e32 v1, v43, v1
	v_pk_fma_f32 v[6:7], v[44:45], v[212:213], v[6:7]
	v_add_f32_e32 v1, v40, v1
	v_pk_fma_f32 v[8:9], v[46:47], v[214:215], v[8:9]
	v_pk_mul_f32 v[46:47], v[6:7], v[6:7]
	v_add_f32_e32 v1, v41, v1
	v_add_f32_e32 v1, v46, v1
	v_pk_mul_f32 v[44:45], v[8:9], v[8:9]
	v_add_f32_e32 v1, v47, v1
	v_add_f32_e32 v1, v44, v1
	v_add_f32_e32 v1, v45, v1
	ds_bpermute_b32 v2, v57, v1
	s_waitcnt lgkmcnt(0)
	v_add_f32_e32 v1, v1, v2
	ds_bpermute_b32 v2, v58, v1
	s_waitcnt lgkmcnt(0)
	v_add_f32_e32 v1, v1, v2
	ds_bpermute_b32 v2, v59, v1
	s_waitcnt lgkmcnt(0)
	v_add_f32_e32 v1, v1, v2
	ds_bpermute_b32 v2, v60, v1
	s_waitcnt lgkmcnt(0)
	v_add_f32_e32 v1, v1, v2
	ds_bpermute_b32 v2, v61, v1
	s_waitcnt lgkmcnt(0)
	v_add_f32_e32 v1, v1, v2
	ds_bpermute_b32 v2, v62, v1
	s_waitcnt lgkmcnt(0)
	v_add_f32_e32 v1, v1, v2
	v_fmamk_f32 v1, v1, 0x3a800000, v63
	v_mul_f32_e32 v2, 0x4b800000, v1
	v_cmp_gt_f32_e32 vcc, s7, v1
	s_nop 1
	v_cndmask_b32_e32 v1, v1, v2, vcc
	v_rsq_f32_e32 v1, v1
	s_nop 0
	v_mul_f32_e32 v2, 0x45800000, v1
	v_cndmask_b32_e32 v36, v1, v2, vcc
	v_pk_mul_f32 v[2:3], v[14:15], v[36:37] op_sel_hi:[1,0]
	v_pk_mul_f32 v[4:5], v[16:17], v[36:37] op_sel_hi:[1,0]
	v_pk_mul_f32 v[2:3], v[216:217], v[2:3]
	v_pk_mul_f32 v[4:5], v[218:219], v[4:5]
	v_cvt_pk_bf16_f32 v2, v2, v3
	v_cvt_pk_bf16_f32 v3, v4, v5
	global_store_dwordx2 v[30:31], v[2:3], off offset:2048
	v_pk_mul_f32 v[10:11], v[10:11], v[36:37] op_sel_hi:[1,0]
	v_pk_mul_f32 v[12:13], v[12:13], v[36:37] op_sel_hi:[1,0]
	v_pk_mul_f32 v[6:7], v[6:7], v[36:37] op_sel_hi:[1,0]
	v_pk_mul_f32 v[8:9], v[8:9], v[36:37] op_sel_hi:[1,0]
	v_cmp_lt_i32_e32 vcc, s17, v18
	s_or_b64 s[14:15], vcc, s[14:15]
	v_pk_mul_f32 v[2:3], v[220:221], v[10:11]
	v_pk_mul_f32 v[4:5], v[222:223], v[12:13]
	v_cvt_pk_bf16_f32 v2, v2, v3
	v_cvt_pk_bf16_f32 v3, v4, v5
	global_store_dwordx2 v[30:31], v[2:3], off offset:2560
	v_pk_mul_f32 v[10:11], v[34:35], v[36:37] op_sel_hi:[1,0]
	v_pk_mul_f32 v[12:13], v[32:33], v[36:37] op_sel_hi:[1,0]
	v_pk_mul_f32 v[2:3], v[224:225], v[10:11]
	v_pk_mul_f32 v[4:5], v[226:227], v[12:13]
	v_cvt_pk_bf16_f32 v2, v2, v3
	v_cvt_pk_bf16_f32 v3, v4, v5
	global_store_dwordx2 v[30:31], v[2:3], off offset:3072
	s_nop 1
	v_pk_mul_f32 v[2:3], v[228:229], v[6:7]
	v_pk_mul_f32 v[4:5], v[230:231], v[8:9]
	v_cvt_pk_bf16_f32 v2, v2, v3
	v_cvt_pk_bf16_f32 v3, v4, v5
	global_store_dwordx2 v[30:31], v[2:3], off offset:3584
	s_andn2_b64 exec, exec, s[14:15]
	s_cbranch_execz .LBB0_708
; DI float bflo(unsigned u) { return __uint_as_float(u << 16); }
; DI float bfhi(unsigned u) { return __uint_as_float(u & 0xffff0000u); }
; DI void phase6(const Params& p) {
;     ...
;     for (int row = VBLK * 4 + w; row < T; row += VGRID * 4) {
;         f32x4 mv[4], xv[4]; float ss = 0.f;
; #pragma unroll
;         for (int i = 0; i < 4; ++i) {
;             const u32x2 u = *(const u32x2*)(MIX + (size_t)row * 1024 + i * 256 + lane * 4);
;             mv[i][0] = bflo(u.x); mv[i][1] = bfhi(u.x); mv[i][2] = bflo(u.y); mv[i][3] = bfhi(u.y);
;             xv[i] = *(const f32x4*)(x + (size_t)row * 1024 + i * 256 + lane * 4);
;             ss += mv[i][0] * mv[i][0] + mv[i][1] * mv[i][1] + mv[i][2] * mv[i][2] + mv[i][3] * mv[i][3];
;         }
;         ss = wave_sum(ss);
;         const float rstd = rsqrtf(ss * (1.f / 1024.f) + NORM_EPS);
;         if (lane == 0) RSTD[row] = rstd;
.LBB0_706:
	s_waitcnt vmcnt(4)
.Lp6_in:
	v_lshl_add_u64 v[30:31], s[88:89], 0, v[26:27]
	v_mov_b32_e32 v34, v70
	v_mov_b32_e32 v35, v71
	v_mov_b32_e32 v38, v72
	v_mov_b32_e32 v39, v73
	v_mov_b32_e32 v42, v74
	v_mov_b32_e32 v43, v75
	v_mov_b32_e32 v54, v76
	v_mov_b32_e32 v55, v77
	v_mov_b32_e32 v14, v80
	v_mov_b32_e32 v15, v81
	v_mov_b32_e32 v16, v82
	v_mov_b32_e32 v17, v83
	v_mov_b32_e32 v10, v84
	v_mov_b32_e32 v11, v85
	v_mov_b32_e32 v12, v86
	v_mov_b32_e32 v13, v87
	v_mov_b32_e32 v2, v88
	v_mov_b32_e32 v3, v89
	v_mov_b32_e32 v4, v90
	v_mov_b32_e32 v5, v91
	v_mov_b32_e32 v6, v92
	v_mov_b32_e32 v7, v93
	v_mov_b32_e32 v8, v94
	v_mov_b32_e32 v9, v95
	v_add_u32_e32 v98, s6, v18
	v_cmp_ge_i32_e32 vcc, s17, v98
	s_and_saveexec_b64 s[98:99], vcc
	s_cbranch_execz .Lp6_nopf
	v_lshl_add_u64 v[96:97], v[30:31], 0, s[10:11]
	v_add_co_u32_e32 v96, vcc, 0x9ba5000, v96
	s_nop 1
	v_addc_co_u32_e32 v97, vcc, 0, v97, vcc
	v_lshl_add_u64 v[98:99], v[28:29], 0, s[12:13]
	global_load_dwordx2 v[70:71], v[96:97], off offset:2048
	global_load_dwordx2 v[72:73], v[96:97], off offset:2560
	global_load_dwordx2 v[74:75], v[96:97], off offset:3072
	global_load_dwordx2 v[76:77], v[96:97], off offset:3584
	global_load_dwordx4 v[80:83], v[98:99], off offset:-3072
	global_load_dwordx4 v[84:87], v[98:99], off offset:-2048
	global_load_dwordx4 v[88:91], v[98:99], off offset:-1024
	global_load_dwordx4 v[92:95], v[98:99], off
.Lp6_nopf:
	s_or_b64 exec, exec, s[98:99]
	v_and_b32_e32 v1, 0xffff0000, v34
	v_lshlrev_b32_e32 v36, 16, v38
	v_and_b32_e32 v49, 0xffff0000, v38
	v_and_b32_e32 v45, 0xffff0000, v42
	v_mov_b32_e32 v48, v1
	v_lshlrev_b32_e32 v32, 16, v34
	v_lshlrev_b32_e32 v38, 16, v39
	v_lshlrev_b32_e32 v44, 16, v54
	v_and_b32_e32 v53, 0xffff0000, v54
	v_mov_b32_e32 v33, v36
	v_mov_b32_e32 v52, v45
	v_pk_mul_f32 v[64:65], v[48:49], v[48:49]
	v_lshlrev_b32_e32 v34, 16, v35
	v_and_b32_e32 v19, 0xffff0000, v35
	v_lshlrev_b32_e32 v40, 16, v42
	v_lshlrev_b32_e32 v46, 16, v55
	v_mov_b32_e32 v35, v38
	v_mov_b32_e32 v41, v44
	v_pk_mul_f32 v[66:67], v[52:53], v[52:53]
	v_pk_fma_f32 v[64:65], v[32:33], v[32:33], v[64:65]
	v_and_b32_e32 v51, 0xffff0000, v39
	v_lshlrev_b32_e32 v42, 16, v43
	v_and_b32_e32 v47, 0xffff0000, v43
	v_mov_b32_e32 v50, v19
	v_mov_b32_e32 v43, v46
	v_pk_fma_f32 v[66:67], v[40:41], v[40:41], v[66:67]
	v_pk_fma_f32 v[64:65], v[34:35], v[34:35], v[64:65]
	v_and_b32_e32 v55, 0xffff0000, v55
	v_mov_b32_e32 v54, v47
	v_pk_fma_f32 v[66:67], v[42:43], v[42:43], v[66:67]
	v_pk_fma_f32 v[64:65], v[50:51], v[50:51], v[64:65]
	v_pk_fma_f32 v[66:67], v[54:55], v[54:55], v[66:67]
	v_add_f32_e32 v33, v64, v65
	v_add_f32_e32 v33, v33, v66
	v_add_f32_e32 v33, v33, v67
	ds_bpermute_b32 v35, v57, v33
	s_waitcnt lgkmcnt(0)
	v_add_f32_e32 v33, v33, v35
	ds_bpermute_b32 v35, v58, v33
	s_waitcnt lgkmcnt(0)
	v_add_f32_e32 v33, v33, v35
	ds_bpermute_b32 v35, v59, v33
	s_waitcnt lgkmcnt(0)
	v_add_f32_e32 v33, v33, v35
	ds_bpermute_b32 v35, v60, v33
	s_waitcnt lgkmcnt(0)
	v_add_f32_e32 v33, v33, v35
	ds_bpermute_b32 v35, v61, v33
	s_waitcnt lgkmcnt(0)
	v_add_f32_e32 v33, v33, v35
	ds_bpermute_b32 v35, v62, v33
	s_waitcnt lgkmcnt(0)
	v_add_f32_e32 v33, v33, v35
	v_fmamk_f32 v33, v33, 0x3a800000, v63
	v_mul_f32_e32 v35, 0x4b800000, v33
	v_cmp_gt_f32_e32 vcc, s7, v33
	s_nop 1
	v_cndmask_b32_e32 v33, v33, v35, vcc
	v_rsq_f32_e32 v33, v33
	s_nop 0
	v_mul_f32_e32 v35, 0x45800000, v33
	v_cndmask_b32_e32 v48, v33, v35, vcc
	s_and_saveexec_b64 s[4:5], s[0:1]
	s_cbranch_execz .LBB0_705
	v_lshl_add_u64 v[64:65], s[88:89], 0, v[24:25]
	global_store_dword v[64:65], v48, off
	s_branch .LBB0_705
